# HGRN scan: MFMA operands fetched with ds_read_b64_tr_b16 from the row-major LDS images; staging waves no longer write transposed copies
# speedup vs baseline: 1.0042x; 1.0006x over previous
; DI void hgrn_scan_mfma(const Params& p, char* shm) {
;     ...
;     for (int u = bx; u < 128; u += gridDim.x) {
;         const int dir = u & 1, head = (u >> 1) & 7, b = u >> 4;
;         const unsigned char* Fb = P + (dir ? P_HF1 : P_HF0); bf16_t* Oo = dir ? (bf16_t*)(p.ws + WS_P + P_HOB) : (bf16_t*)(p.ws + WS_H);
;         f32x4 S[8];
; #pragma unroll
;         for (int kt = 0; kt < 8; ++kt) S[kt] = (f32x4){0.f, 0.f, 0.f, 0.f};
;         const int lt = tid >> 4, lp = tid & 15;
;         u32x4 ra0, ra1, ra2, ra3, ra4, rb0, rb1, rb2, rb3, rb4;
.LBB0_2416:
	s_or_b64 exec, exec, s[14:15]
	v_cndmask_b32_e64 v3, 0, 1, s[40:41]
	v_lshl_add_u64 v[142:143], s[0:1], 0, v[0:1]
	v_readfirstlane_b32 s14, v3
	s_lshl_b32 s55, s14, 3
	s_lshl_b32 s14, s31, 2
	s_and_b32 s56, s14, 0xe00
	s_and_b64 s[14:15], s[12:13], exec
	s_cselect_b32 s14, s72, 0x146da000
	s_add_u32 s14, s68, s14
	s_addc_u32 s15, s69, 0
	s_add_u32 s14, s14, s38
	s_addc_u32 s15, s15, 0
	v_lshl_add_u64 v[132:133], v[120:121], 1, s[14:15]
	s_and_b64 s[14:15], s[12:13], exec
	s_cselect_b32 s15, 0, -1
	s_cselect_b32 s14, s73, 0xfffffc00
	s_add_i32 s0, s54, s55
	s_mul_hi_i32 s1, s0, 0x48000
	s_mul_i32 s0, s0, 0x48000
	s_or_b32 s0, s0, s56
	v_mov_b32_e32 v44, 0
	s_mov_b32 s74, 0
	v_lshl_add_u64 v[128:129], v[116:117], 0, s[38:39]
	v_lshl_add_u64 v[130:131], v[118:119], 0, s[38:39]
	v_mul_hi_i32_i24_e32 v135, s14, v147
	v_mul_i32_i24_e32 v134, s14, v147
	s_lshl_b64 s[52:53], s[14:15], 5
	v_mul_hi_i32_i24_e32 v137, s14, v152
	v_mul_i32_i24_e32 v136, s14, v152
	v_mul_hi_i32_i24_e32 v139, s14, v153
	v_mul_i32_i24_e32 v138, s14, v153
	v_mul_hi_i32_i24_e32 v141, s14, v154
	v_mul_i32_i24_e32 v140, s14, v154
	v_lshl_add_u64 v[144:145], v[122:123], 0, s[0:1]
	s_movk_i32 s38, 0xffe0
	s_mov_b32 s76, 0
	v_mov_b32_e32 v45, v44
	v_mov_b32_e32 v46, v44
	v_mov_b32_e32 v47, v44
	v_mov_b32_e32 v48, v44
	v_mov_b32_e32 v49, v44
	v_mov_b32_e32 v50, v44
	v_mov_b32_e32 v51, v44
	v_mov_b32_e32 v52, v44
	v_mov_b32_e32 v53, v44
	v_mov_b32_e32 v54, v44
	v_mov_b32_e32 v55, v44
	v_mov_b32_e32 v56, v44
	v_mov_b32_e32 v57, v44
	v_mov_b32_e32 v58, v44
	v_mov_b32_e32 v59, v44
	v_mov_b32_e32 v60, v44
	v_mov_b32_e32 v61, v44
	v_mov_b32_e32 v62, v44
	v_mov_b32_e32 v63, v44
	v_mov_b32_e32 v64, v44
	v_mov_b32_e32 v65, v44
	v_mov_b32_e32 v66, v44
	v_mov_b32_e32 v67, v44
	v_mov_b32_e32 v72, v44
	v_mov_b32_e32 v73, v44
	v_mov_b32_e32 v74, v44
	v_mov_b32_e32 v75, v44
	v_mov_b32_e32 v68, v44
	v_mov_b32_e32 v69, v44
	v_mov_b32_e32 v70, v44
	v_mov_b32_e32 v71, v44
	s_cmp_lg_u32 s100, 0
	s_cbranch_scc1 .Lscanh_pro
	v_add_u32_e32 v195, 0x8000, v161
	v_add_u32_e32 v197, 0x9000, v161
	v_bfe_u32 v200, v252, 4, 2
	v_bfe_u32 v201, v252, 2, 2
	v_lshl_add_u32 v200, v200, 2, v201
	v_mul_u32_u24_e32 v199, 0x110, v200
	v_and_b32_e32 v201, 3, v252
	v_lshl_add_u32 v199, v201, 3, v199
	v_and_b32_e32 v198, -16, v120
	v_lshl_add_u32 v198, v198, 1, v199

; DI unsigned pack2(float lo, float hi) { const f32x2 v = (f32x2){lo, hi}; return __builtin_bit_cast(unsigned, __builtin_convertvector(v, bf16x2_t)); }
; DI void hgrn_scan_mfma(const Params& p, char* shm) {
;     ...
;             { const bf16_t* kt16 = (const bf16_t*)KtL; const bf16_t* v16 = (const bf16_t*)VL; const int vcol = w * 16 + l15;
;     ...
;               const bf16x8 vf = __builtin_bit_cast(bf16x8, (u32x4){HG_U2(v16, g * 4 + 0, g * 4 + 1, vcol), HG_U2(v16, g * 4 + 2, g * 4 + 3, vcol), HG_U2(v16, 16 + g * 4 + 0, 16 + g * 4 + 1, vcol), HG_U2(v16, 16 + g * 4 + 2, 16 + g * 4 + 3, vcol)});
;               f32x4 sc00 = (f32x4){0.f, 0.f, 0.f, 0.f}, sc01 = sc00, sc11 = sc00, o0 = sc00, o1 = sc00;
; #pragma unroll
;               for (int kc = 0; kc < 4; ++kc) {
;                   const bf16x8 aK0 = *(const bf16x8*)(KtL + l15 * QS + kc * 64 + g * 16), aK1 = *(const bf16x8*)(KtL + (16 + l15) * QS + kc * 64 + g * 16);
;                   const bf16x8 bQ0 = *(const bf16x8*)(QtL + l15 * QS + kc * 64 + g * 16), bQ1 = *(const bf16x8*)(QtL + (16 + l15) * QS + kc * 64 + g * 16);
;                   sc00 = __builtin_amdgcn_mfma_f32_16x16x32_bf16(aK0, bQ0, sc00, 0, 0, 0);
;                   sc01 = __builtin_amdgcn_mfma_f32_16x16x32_bf16(aK0, bQ1, sc01, 0, 0, 0);
;                   sc11 = __builtin_amdgcn_mfma_f32_16x16x32_bf16(aK1, bQ1, sc11, 0, 0, 0);
;                   const int kp = kc;
;                   const u32x2 qa0 = *(const u32x2*)(QtL + l15 * QS + ((2 * kp) * 16 + g * 4) * 2), qb0 = *(const u32x2*)(QtL + l15 * QS + ((2 * kp + 1) * 16 + g * 4) * 2);
;                   const u32x2 qa1 = *(const u32x2*)(QtL + (16 + l15) * QS + ((2 * kp) * 16 + g * 4) * 2), qb1 = *(const u32x2*)(QtL + (16 + l15) * QS + ((2 * kp + 1) * 16 + g * 4) * 2);
;                   const bf16x8 sw = __builtin_bit_cast(bf16x8, (u32x4){pack2(S[2 * kp][0], S[2 * kp][1]), pack2(S[2 * kp][2], S[2 * kp][3]), pack2(S[2 * kp + 1][0], S[2 * kp + 1][1]), pack2(S[2 * kp + 1][2], S[2 * kp + 1][3])});
;                   o0 = __builtin_amdgcn_mfma_f32_16x16x32_bf16(__builtin_bit_cast(bf16x8, (u32x4){qa0.x, qa0.y, qb0.x, qb0.y}), sw, o0, 0, 0, 0);
;                   o1 = __builtin_amdgcn_mfma_f32_16x16x32_bf16(__builtin_bit_cast(bf16x8, (u32x4){qa1.x, qa1.y, qb1.x, qb1.y}), sw, o1, 0, 0, 0); }
; #pragma unroll
;               for (int r = 0; r < 4; ++r) if (g * 4 + r > l15) { sc00[r] = 0.f; sc11[r] = 0.f; }
.LBB0_2429:
	ds_read_b128 v[80:83], v160 offset:17408
	ds_read_b128 v[76:79], v160
	ds_read_b128 v[84:87], v160 offset:21760
	ds_read_b128 v[88:91], v160 offset:17472
	ds_read_b128 v[92:95], v160 offset:64
	ds_read_b128 v[96:99], v160 offset:4352
	ds_read_b128 v[100:103], v160 offset:21824
	ds_read_b128 v[104:107], v160 offset:4416
	s_waitcnt lgkmcnt(6)
	v_mfma_f32_16x16x32_bf16 v[76:79], v[80:83], v[76:79], 0
	v_cvt_pk_bf16_f32 v186, v52, v53
	v_cvt_pk_bf16_f32 v187, v54, v55
	v_cvt_pk_bf16_f32 v188, v56, v57
	s_waitcnt lgkmcnt(3)
	v_mfma_f32_16x16x32_bf16 v[76:79], v[88:91], v[92:95], v[76:79]
	ds_read_b128 v[92:95], v160 offset:17536
	ds_read_b128 v[108:111], v160 offset:128
	v_cvt_pk_bf16_f32 v189, v58, v59
	s_cmp_lt_u32 s76, 8
	s_waitcnt lgkmcnt(4)
	v_mfma_f32_16x16x32_bf16 v[84:87], v[84:87], v[96:99], 0
	s_cselect_b32 s77, 0xff, s58
	s_add_i32 s77, s77, s38
	s_add_i32 s78, s77, 32
	s_waitcnt lgkmcnt(2)
	v_mfma_f32_16x16x32_bf16 v[84:87], v[100:103], v[104:107], v[84:87]
	ds_read_b128 v[100:103], v160 offset:21888
	ds_read_b128 v[162:165], v160 offset:17600
	ds_read_b128 v[166:169], v160 offset:192
	ds_read_b128 v[170:173], v160 offset:4480
	ds_read_b128 v[174:177], v160 offset:21952
	ds_read_b128 v[178:181], v160 offset:4544
	s_and_b64 s[14:15], s[12:13], exec
	s_waitcnt lgkmcnt(6)
	v_mfma_f32_16x16x32_bf16 v[108:111], v[92:95], v[108:111], v[76:79]
	ds_read_b64_tr_b16 v[76:77], v198 offset:8704
	ds_read_b64_tr_b16 v[78:79], v198 offset:13056
	v_mov_b32_e32 v0, s39
	s_waitcnt lgkmcnt(4)
	v_mfma_f32_16x16x32_bf16 v[84:87], v[100:103], v[170:173], v[84:87]
	v_add_u32_e32 v125, 0x1000, v161
	v_mfma_f32_16x16x32_bf16 v[100:103], v[162:165], v[166:169], v[108:111]
	ds_read2_b64 v[166:169], v125 offset0:32 offset1:36
	s_cselect_b32 s14, s74, s78
	ds_read2_b64 v[108:111], v161 offset1:4
	v_mfma_f32_16x16x32_bf16 v[80:83], v[80:83], v[96:99], 0
	s_nop 2
	s_nop 0
	v_cndmask_b32_e64 v0, v100, v0, s[4:5]
	v_cndmask_b32_e64 v0, v0, v100, s[6:7]
	v_cndmask_b32_e64 v3, v102, 0, s[8:9]
	s_waitcnt lgkmcnt(4)
	v_mfma_f32_16x16x32_bf16 v[84:87], v[174:177], v[178:181], v[84:87]
	v_cvt_pk_bf16_f32 v174, v44, v45
	v_cvt_pk_bf16_f32 v175, v46, v47
	v_cvt_pk_bf16_f32 v176, v48, v49
	v_cvt_pk_bf16_f32 v177, v50, v51
	v_mfma_f32_16x16x32_bf16 v[80:83], v[88:91], v[104:107], v[80:83]
	s_add_u32 s14, s50, s14
	s_addc_u32 s15, s51, 0
	s_lshl_b64 s[14:15], s[14:15], 11
	s_waitcnt lgkmcnt(0)
	v_mfma_f32_16x16x32_bf16 v[96:99], v[108:111], v[174:177], 0
	ds_read2_b64 v[108:111], v161 offset0:8 offset1:12
	ds_read2_b64 v[182:185], v125 offset0:40 offset1:44
	ds_read2_b64 v[88:91], v161 offset0:16 offset1:20
	ds_read2_b64 v[104:107], v125 offset0:48 offset1:52
	v_mfma_f32_16x16x32_bf16 v[166:169], v[166:169], v[174:177], 0
	v_cvt_pk_bf16_f32 v174, v60, v61
	v_cvt_pk_bf16_f32 v175, v62, v63
	v_cvt_pk_bf16_f32 v176, v64, v65
	s_waitcnt lgkmcnt(3)
	v_mfma_f32_16x16x32_bf16 v[96:99], v[108:111], v[186:189], v[96:99]
	v_cvt_pk_bf16_f32 v177, v66, v67
	v_mfma_f32_16x16x32_bf16 v[80:83], v[92:95], v[170:173], v[80:83]
	v_mov_b32_e32 v92, s39
	v_cndmask_b32_e64 v1, v84, v92, s[4:5]
	s_waitcnt lgkmcnt(2)
	v_mfma_f32_16x16x32_bf16 v[108:111], v[182:185], v[186:189], v[166:169]
	s_nop 2
	ds_read2_b64 v[166:169], v161 offset0:24 offset1:28
	ds_read2_b64 v[182:185], v125 offset0:56 offset1:60
	v_cvt_pk_bf16_f32 v186, v72, v73
	v_cvt_pk_bf16_f32 v187, v74, v75
	s_waitcnt lgkmcnt(3)
	v_mfma_f32_16x16x32_bf16 v[88:91], v[88:91], v[174:177], v[96:99]
	v_cvt_pk_bf16_f32 v188, v68, v69
	v_cvt_pk_bf16_f32 v189, v70, v71
	v_mfma_f32_16x16x32_bf16 v[80:83], v[162:165], v[178:181], v[80:83]
	v_cndmask_b32_e64 v96, v1, v84, s[6:7]
	v_cndmask_b32_e64 v1, 0, v101, s[6:7]
	v_cndmask_b32_e64 v84, v103, 0, s[10:11]
	s_waitcnt lgkmcnt(2)
	v_mfma_f32_16x16x32_bf16 v[92:95], v[104:107], v[174:177], v[108:111]
	v_cvt_pk_bf16_f32 v0, v0, v1
	v_cvt_pk_bf16_f32 v1, v3, v84
	v_mov_b32_e32 v3, v2
	v_cndmask_b32_e64 v97, 0, v85, s[6:7]
	v_cndmask_b32_e64 v98, v86, 0, s[8:9]
	v_cndmask_b32_e64 v99, v87, 0, s[10:11]
	s_waitcnt lgkmcnt(1)
	v_mfma_f32_16x16x32_bf16 v[88:91], v[166:169], v[186:189], v[88:91]
	v_cvt_pk_bf16_f32 v80, v80, v81
	v_cvt_pk_bf16_f32 v81, v82, v83
	v_cvt_pk_bf16_f32 v82, v96, v97
	v_cvt_pk_bf16_f32 v83, v98, v99
	s_waitcnt lgkmcnt(0)
	v_mfma_f32_16x16x32_bf16 v[92:95], v[182:185], v[186:189], v[92:95]
	v_mfma_f32_16x16x32_bf16 v[84:87], v[0:3], v[76:79], v[88:91]
	v_lshl_add_u64 v[0:1], v[132:133], 0, s[14:15]
	v_mfma_f32_16x16x32_bf16 v[80:83], v[80:83], v[76:79], v[92:95]
	s_nop 0
	v_lshl_add_u64 v[88:89], v[134:135], 1, v[0:1]
	s_nop 3
	v_cvt_pk_bf16_f32 v3, v84, s0
	global_store_short v[88:89], v3, off
	v_lshl_add_u64 v[88:89], v[88:89], 0, s[52:53]
	v_cvt_pk_bf16_f32 v3, v80, s0
	global_store_short v[88:89], v3, off
	v_lshl_add_u64 v[88:89], v[136:137], 1, v[0:1]
	v_cvt_pk_bf16_f32 v3, v85, s0
	global_store_short v[88:89], v3, off
	v_cvt_pk_bf16_f32 v3, v81, s0
	v_lshl_add_u64 v[80:81], v[88:89], 0, s[52:53]
	global_store_short v[80:81], v3, off
	v_lshl_add_u64 v[80:81], v[138:139], 1, v[0:1]
	v_cvt_pk_bf16_f32 v3, v86, s0
	global_store_short v[80:81], v3, off
	ds_read_b64_tr_b16 v[200:201], v199 offset:17408
	ds_read_b64_tr_b16 v[202:203], v199 offset:21760
	ds_read_b64_tr_b16 v[204:205], v199 offset:17440
	ds_read_b64_tr_b16 v[206:207], v199 offset:21792
	ds_read_b64_tr_b16 v[208:209], v199 offset:17472
	ds_read_b64_tr_b16 v[210:211], v199 offset:21824
	ds_read_b64_tr_b16 v[212:213], v199 offset:17504
	ds_read_b64_tr_b16 v[214:215], v199 offset:21856
	ds_read_b64_tr_b16 v[216:217], v199 offset:17536
	ds_read_b64_tr_b16 v[218:219], v199 offset:21888
	ds_read_b64_tr_b16 v[220:221], v199 offset:17568
	ds_read_b64_tr_b16 v[222:223], v199 offset:21920
	ds_read_b64_tr_b16 v[224:225], v199 offset:17600
	ds_read_b64_tr_b16 v[226:227], v199 offset:21952
	ds_read_b64_tr_b16 v[228:229], v199 offset:17632
	ds_read_b64_tr_b16 v[230:231], v199 offset:21984
	s_waitcnt lgkmcnt(14)
; DI unsigned pack2(float lo, float hi) { const f32x2 v = (f32x2){lo, hi}; return __builtin_bit_cast(unsigned, __builtin_convertvector(v, bf16x2_t)); }
; DI void hgrn_scan_mfma(const Params& p, char* shm) {
;     ...
;             { const bf16_t* kt16 = (const bf16_t*)KtL; const bf16_t* v16 = (const bf16_t*)VL; const int vcol = w * 16 + l15;
;     ...
;               const bf16x8 vf = __builtin_bit_cast(bf16x8, (u32x4){HG_U2(v16, g * 4 + 0, g * 4 + 1, vcol), HG_U2(v16, g * 4 + 2, g * 4 + 3, vcol), HG_U2(v16, 16 + g * 4 + 0, 16 + g * 4 + 1, vcol), HG_U2(v16, 16 + g * 4 + 2, 16 + g * 4 + 3, vcol)});
;               f32x4 sc00 = (f32x4){0.f, 0.f, 0.f, 0.f}, sc01 = sc00, sc11 = sc00, o0 = sc00, o1 = sc00;
; #pragma unroll
;               for (int kc = 0; kc < 4; ++kc) {
;                   const bf16x8 aK0 = *(const bf16x8*)(KtL + l15 * QS + kc * 64 + g * 16), aK1 = *(const bf16x8*)(KtL + (16 + l15) * QS + kc * 64 + g * 16);
;                   const bf16x8 bQ0 = *(const bf16x8*)(QtL + l15 * QS + kc * 64 + g * 16), bQ1 = *(const bf16x8*)(QtL + (16 + l15) * QS + kc * 64 + g * 16);
;                   sc00 = __builtin_amdgcn_mfma_f32_16x16x32_bf16(aK0, bQ0, sc00, 0, 0, 0);
;                   sc01 = __builtin_amdgcn_mfma_f32_16x16x32_bf16(aK0, bQ1, sc01, 0, 0, 0);
;                   sc11 = __builtin_amdgcn_mfma_f32_16x16x32_bf16(aK1, bQ1, sc11, 0, 0, 0);
;                   const int kp = kc;
;                   const u32x2 qa0 = *(const u32x2*)(QtL + l15 * QS + ((2 * kp) * 16 + g * 4) * 2), qb0 = *(const u32x2*)(QtL + l15 * QS + ((2 * kp + 1) * 16 + g * 4) * 2);
;                   const u32x2 qa1 = *(const u32x2*)(QtL + (16 + l15) * QS + ((2 * kp) * 16 + g * 4) * 2), qb1 = *(const u32x2*)(QtL + (16 + l15) * QS + ((2 * kp + 1) * 16 + g * 4) * 2);
;                   const bf16x8 sw = __builtin_bit_cast(bf16x8, (u32x4){pack2(S[2 * kp][0], S[2 * kp][1]), pack2(S[2 * kp][2], S[2 * kp][3]), pack2(S[2 * kp + 1][0], S[2 * kp + 1][1]), pack2(S[2 * kp + 1][2], S[2 * kp + 1][3])});
;                   o0 = __builtin_amdgcn_mfma_f32_16x16x32_bf16(__builtin_bit_cast(bf16x8, (u32x4){qa0.x, qa0.y, qb0.x, qb0.y}), sw, o0, 0, 0, 0);
;                   o1 = __builtin_amdgcn_mfma_f32_16x16x32_bf16(__builtin_bit_cast(bf16x8, (u32x4){qa1.x, qa1.y, qb1.x, qb1.y}), sw, o1, 0, 0, 0); }
; #pragma unroll
;               for (int r = 0; r < 4; ++r) if (g * 4 + r > l15) { sc00[r] = 0.f; sc11[r] = 0.f; }
	v_mfma_f32_16x16x32_bf16 v[44:47], v[200:203], v[76:79], v[44:47]
	v_cvt_pk_bf16_f32 v3, v82, s0
	v_lshl_add_u64 v[80:81], v[80:81], 0, s[52:53]
	global_store_short v[80:81], v3, off
	v_lshl_add_u64 v[0:1], v[140:141], 1, v[0:1]
	v_cvt_pk_bf16_f32 v3, v87, s0
	s_waitcnt lgkmcnt(12)
	v_mfma_f32_16x16x32_bf16 v[48:51], v[204:207], v[76:79], v[48:51]
	s_waitcnt lgkmcnt(10)
	v_mfma_f32_16x16x32_bf16 v[52:55], v[208:211], v[76:79], v[52:55]
	global_store_short v[0:1], v3, off
	v_cvt_pk_bf16_f32 v3, v83, s0
	v_lshl_add_u64 v[0:1], v[0:1], 0, s[52:53]
	s_waitcnt lgkmcnt(8)
	v_mfma_f32_16x16x32_bf16 v[56:59], v[212:215], v[76:79], v[56:59]
	global_store_short v[0:1], v3, off
	s_waitcnt lgkmcnt(6)
	v_mfma_f32_16x16x32_bf16 v[60:63], v[216:219], v[76:79], v[60:63]
	ds_read_b128 v[108:111], v149 offset:26112
	ds_read_b128 v[104:107], v149 offset:26176
	ds_read_b128 v[100:103], v149 offset:26240
	ds_read_b128 v[96:99], v149 offset:26304
	s_waitcnt lgkmcnt(8)
	v_mfma_f32_16x16x32_bf16 v[64:67], v[220:223], v[76:79], v[64:67]
	s_waitcnt lgkmcnt(6)
	v_mfma_f32_16x16x32_bf16 v[80:83], v[224:227], v[76:79], v[72:75]
	ds_read_b128 v[92:95], v149 offset:26368
	ds_read_b128 v[88:91], v149 offset:26432
	ds_read_b128 v[84:87], v149 offset:26496
	ds_read_b128 v[72:75], v149 offset:26560
	s_waitcnt lgkmcnt(0)
	s_barrier
	v_mfma_f32_16x16x32_bf16 v[76:79], v[228:231], v[76:79], v[68:71]
	s_nop 0
	s_nop 0
	s_and_saveexec_b64 s[14:15], s[2:3]
	s_or_b64 exec, exec, s[14:15]
	s_andn2_b64 vcc, exec, s[56:57]
	s_branch .LBB0_2441
.LBB0_2441:
	v_pk_mul_f32 v[58:59], v[98:99], v[58:59]
	v_pk_mul_f32 v[56:57], v[96:97], v[56:57]
	ds_read_b128 v[96:99], v160 offset:50176
	v_pk_mul_f32 v[62:63], v[94:95], v[62:63]
	v_pk_mul_f32 v[60:61], v[92:93], v[60:61]
	ds_read_b128 v[68:71], v160 offset:54528
	ds_read_b128 v[92:95], v160 offset:32768
	v_pk_mul_f32 v[46:47], v[110:111], v[46:47]
	v_pk_mul_f32 v[44:45], v[108:109], v[44:45]
	v_pk_mul_f32 v[50:51], v[106:107], v[50:51]
	v_pk_mul_f32 v[48:49], v[104:105], v[48:49]
	v_pk_mul_f32 v[54:55], v[102:103], v[54:55]
	v_pk_mul_f32 v[52:53], v[100:101], v[52:53]
	ds_read_b128 v[100:103], v160 offset:37120
	ds_read_b128 v[104:107], v160 offset:50240
	ds_read_b128 v[108:111], v160 offset:32832
	ds_read_b128 v[162:165], v160 offset:54592
	ds_read_b128 v[166:169], v160 offset:37184
	v_pk_mul_f32 v[66:67], v[90:91], v[66:67]
	s_waitcnt lgkmcnt(5)
	v_mfma_f32_16x16x32_bf16 v[90:93], v[96:99], v[92:95], 0
	v_mul_f32_e64 v64, v88, v64
	v_mul_f32_e64 v65, v89, v65
	v_pk_mul_f32 v[78:79], v[74:75], v[78:79]
	v_pk_mul_f32 v[76:77], v[72:73], v[76:77]
	s_waitcnt lgkmcnt(4)
	v_mfma_f32_16x16x32_bf16 v[170:173], v[68:71], v[100:103], 0
	v_mul_f32_e64 v70, v86, v82
	v_mul_f32_e64 v71, v87, v83
	v_pk_mul_f32 v[68:69], v[84:85], v[80:81]
	ds_read_b128 v[84:87], v160 offset:50304
	s_waitcnt lgkmcnt(3)
	v_mfma_f32_16x16x32_bf16 v[80:83], v[104:107], v[108:111], v[90:93]
	s_nop 2
	ds_read_b128 v[88:91], v160 offset:54656
	ds_read_b128 v[92:95], v160 offset:32896
	v_cvt_pk_bf16_f32 v186, v52, v53
	v_cvt_pk_bf16_f32 v187, v54, v55
	s_waitcnt lgkmcnt(3)
	v_mfma_f32_16x16x32_bf16 v[108:111], v[162:165], v[166:169], v[170:173]
	ds_read_b128 v[162:165], v160 offset:37248
	s_nop 1
	ds_read_b128 v[170:173], v160 offset:50368
	ds_read_b128 v[174:177], v160 offset:32960
	ds_read_b128 v[72:75], v160 offset:54720
	ds_read_b128 v[178:181], v160 offset:37312
	v_cvt_pk_bf16_f32 v188, v56, v57
	s_waitcnt lgkmcnt(4)
	v_mfma_f32_16x16x32_bf16 v[88:91], v[88:91], v[162:165], v[108:111]
	v_cvt_pk_bf16_f32 v189, v58, v59
	s_add_i32 s14, s74, 32
	s_and_b64 s[0:1], s[12:13], exec
	v_mfma_f32_16x16x32_bf16 v[92:95], v[84:87], v[92:95], v[80:83]
	ds_read_b64_tr_b16 v[80:81], v198 offset:41472
	ds_read_b64_tr_b16 v[82:83], v198 offset:45824
	ds_read2_b64 v[108:111], v195 offset1:4
	s_waitcnt lgkmcnt(3)
	v_mfma_f32_16x16x32_bf16 v[72:75], v[72:75], v[178:181], v[88:91]
	v_mov_b32_e32 v0, s39
	ds_read2_b64 v[88:91], v197 offset0:32 offset1:36
	v_mfma_f32_16x16x32_bf16 v[96:99], v[96:99], v[100:103], 0
	s_cselect_b32 s0, s14, s77
	s_add_u32 s0, s50, s0
	v_mfma_f32_16x16x32_bf16 v[92:95], v[170:173], v[174:177], v[92:95]
	v_cvt_pk_bf16_f32 v174, v44, v45
	v_cvt_pk_bf16_f32 v175, v46, v47
	v_cvt_pk_bf16_f32 v176, v48, v49
	v_cvt_pk_bf16_f32 v177, v50, v51
	v_mfma_f32_16x16x32_bf16 v[96:99], v[104:107], v[166:169], v[96:99]
	s_nop 2
	v_cndmask_b32_e64 v0, v92, v0, s[4:5]
	v_cndmask_b32_e64 v0, v0, v92, s[6:7]
	v_cndmask_b32_e64 v3, v94, 0, s[8:9]
	s_waitcnt lgkmcnt(1)
	v_mfma_f32_16x16x32_bf16 v[100:103], v[108:111], v[174:177], 0
	ds_read2_b64 v[108:111], v195 offset0:8 offset1:12
	ds_read2_b64 v[182:185], v197 offset0:40 offset1:44
	ds_read2_b64 v[104:107], v195 offset0:16 offset1:20
	ds_read2_b64 v[166:169], v197 offset0:48 offset1:52
	s_addc_u32 s1, s51, 0
	s_waitcnt lgkmcnt(4)
	v_mfma_f32_16x16x32_bf16 v[88:91], v[88:91], v[174:177], 0
	v_cvt_pk_bf16_f32 v174, v60, v61
	v_cvt_pk_bf16_f32 v175, v62, v63
	v_cvt_pk_bf16_f32 v176, v64, v65
	s_waitcnt lgkmcnt(3)
	v_mfma_f32_16x16x32_bf16 v[100:103], v[108:111], v[186:189], v[100:103]
	v_cvt_pk_bf16_f32 v177, v66, v67
	s_lshl_b64 s[0:1], s[0:1], 11
	v_mfma_f32_16x16x32_bf16 v[84:87], v[84:87], v[162:165], v[96:99]
	s_sub_i32 s38, s38, 64
	s_add_i32 s74, s74, 64
	s_and_b64 vcc, exec, s[54:55]
	s_waitcnt lgkmcnt(2)
; DI unsigned pack2(float lo, float hi) { const f32x2 v = (f32x2){lo, hi}; return __builtin_bit_cast(unsigned, __builtin_convertvector(v, bf16x2_t)); }
; DI void hgrn_scan_mfma(const Params& p, char* shm) {
;     ...
;             { const bf16_t* kt16 = (const bf16_t*)KtL; const bf16_t* v16 = (const bf16_t*)VL; const int vcol = w * 16 + l15;
;     ...
;               const bf16x8 vf = __builtin_bit_cast(bf16x8, (u32x4){HG_U2(v16, g * 4 + 0, g * 4 + 1, vcol), HG_U2(v16, g * 4 + 2, g * 4 + 3, vcol), HG_U2(v16, 16 + g * 4 + 0, 16 + g * 4 + 1, vcol), HG_U2(v16, 16 + g * 4 + 2, 16 + g * 4 + 3, vcol)});
;               f32x4 sc00 = (f32x4){0.f, 0.f, 0.f, 0.f}, sc01 = sc00, sc11 = sc00, o0 = sc00, o1 = sc00;
; #pragma unroll
;               for (int kc = 0; kc < 4; ++kc) {
;                   const bf16x8 aK0 = *(const bf16x8*)(KtL + l15 * QS + kc * 64 + g * 16), aK1 = *(const bf16x8*)(KtL + (16 + l15) * QS + kc * 64 + g * 16);
;                   const bf16x8 bQ0 = *(const bf16x8*)(QtL + l15 * QS + kc * 64 + g * 16), bQ1 = *(const bf16x8*)(QtL + (16 + l15) * QS + kc * 64 + g * 16);
;                   sc00 = __builtin_amdgcn_mfma_f32_16x16x32_bf16(aK0, bQ0, sc00, 0, 0, 0);
;                   sc01 = __builtin_amdgcn_mfma_f32_16x16x32_bf16(aK0, bQ1, sc01, 0, 0, 0);
;                   sc11 = __builtin_amdgcn_mfma_f32_16x16x32_bf16(aK1, bQ1, sc11, 0, 0, 0);
;                   const int kp = kc;
;                   const u32x2 qa0 = *(const u32x2*)(QtL + l15 * QS + ((2 * kp) * 16 + g * 4) * 2), qb0 = *(const u32x2*)(QtL + l15 * QS + ((2 * kp + 1) * 16 + g * 4) * 2);
;                   const u32x2 qa1 = *(const u32x2*)(QtL + (16 + l15) * QS + ((2 * kp) * 16 + g * 4) * 2), qb1 = *(const u32x2*)(QtL + (16 + l15) * QS + ((2 * kp + 1) * 16 + g * 4) * 2);
;                   const bf16x8 sw = __builtin_bit_cast(bf16x8, (u32x4){pack2(S[2 * kp][0], S[2 * kp][1]), pack2(S[2 * kp][2], S[2 * kp][3]), pack2(S[2 * kp + 1][0], S[2 * kp + 1][1]), pack2(S[2 * kp + 1][2], S[2 * kp + 1][3])});
;                   o0 = __builtin_amdgcn_mfma_f32_16x16x32_bf16(__builtin_bit_cast(bf16x8, (u32x4){qa0.x, qa0.y, qb0.x, qb0.y}), sw, o0, 0, 0, 0);
;                   o1 = __builtin_amdgcn_mfma_f32_16x16x32_bf16(__builtin_bit_cast(bf16x8, (u32x4){qa1.x, qa1.y, qb1.x, qb1.y}), sw, o1, 0, 0, 0); }
; #pragma unroll
;               for (int r = 0; r < 4; ++r) if (g * 4 + r > l15) { sc00[r] = 0.f; sc11[r] = 0.f; }
	v_mfma_f32_16x16x32_bf16 v[88:91], v[182:185], v[186:189], v[88:91]
	ds_read2_b64 v[108:111], v195 offset0:24 offset1:28
	ds_read2_b64 v[182:185], v197 offset0:56 offset1:60
	v_cvt_pk_bf16_f32 v186, v68, v69
	v_cvt_pk_bf16_f32 v187, v70, v71
	s_waitcnt lgkmcnt(3)
	v_mfma_f32_16x16x32_bf16 v[96:99], v[104:107], v[174:177], v[100:103]
	v_cvt_pk_bf16_f32 v188, v76, v77
	v_cvt_pk_bf16_f32 v189, v78, v79
	s_nop 0
	v_mov_b32_e32 v100, s39
	v_mfma_f32_16x16x32_bf16 v[84:87], v[170:173], v[178:181], v[84:87]
	v_cndmask_b32_e64 v1, v72, v100, s[4:5]
	v_cndmask_b32_e64 v100, v1, v72, s[6:7]
	v_cndmask_b32_e64 v1, 0, v93, s[6:7]
	s_waitcnt lgkmcnt(2)
	v_mfma_f32_16x16x32_bf16 v[88:91], v[166:169], v[174:177], v[88:91]
	v_cndmask_b32_e64 v72, v95, 0, s[10:11]
	v_cvt_pk_bf16_f32 v0, v0, v1
	v_cvt_pk_bf16_f32 v1, v3, v72
	s_waitcnt lgkmcnt(1)
	v_mfma_f32_16x16x32_bf16 v[92:95], v[108:111], v[186:189], v[96:99]
	v_mov_b32_e32 v3, v2
	v_cvt_pk_bf16_f32 v84, v84, v85
	v_cvt_pk_bf16_f32 v85, v86, v87
	v_cndmask_b32_e64 v96, 0, v73, s[6:7]
	v_cndmask_b32_e64 v97, v74, 0, s[8:9]
	v_cndmask_b32_e64 v98, v75, 0, s[10:11]
	v_cvt_pk_bf16_f32 v86, v100, v96
	v_cvt_pk_bf16_f32 v87, v97, v98
	s_waitcnt lgkmcnt(0)
	v_mfma_f32_16x16x32_bf16 v[88:91], v[182:185], v[186:189], v[88:91]
	v_mfma_f32_16x16x32_bf16 v[72:75], v[0:3], v[80:83], v[92:95]
	v_lshl_add_u64 v[0:1], v[132:133], 0, s[0:1]
	v_mfma_f32_16x16x32_bf16 v[84:87], v[84:87], v[80:83], v[88:91]
	s_nop 4
	v_lshl_add_u64 v[88:89], v[134:135], 1, v[0:1]
	v_cvt_pk_bf16_f32 v3, v72, s0
	global_store_short v[88:89], v3, off
	v_cvt_pk_bf16_f32 v3, v84, s0
	v_lshl_add_u64 v[88:89], v[88:89], 0, s[52:53]
	global_store_short v[88:89], v3, off
	v_lshl_add_u64 v[88:89], v[136:137], 1, v[0:1]
	v_cvt_pk_bf16_f32 v3, v73, s0
	global_store_short v[88:89], v3, off
	v_cvt_pk_bf16_f32 v3, v85, s0
	v_lshl_add_u64 v[72:73], v[88:89], 0, s[52:53]
	global_store_short v[72:73], v3, off
	v_lshl_add_u64 v[72:73], v[138:139], 1, v[0:1]
	v_cvt_pk_bf16_f32 v3, v74, s0
	global_store_short v[72:73], v3, off
	v_cvt_pk_bf16_f32 v3, v86, s0
	v_lshl_add_u64 v[72:73], v[72:73], 0, s[52:53]
	global_store_short v[72:73], v3, off
	v_lshl_add_u64 v[0:1], v[140:141], 1, v[0:1]
	v_cvt_pk_bf16_f32 v3, v75, s0
	global_store_short v[0:1], v3, off
	v_cvt_pk_bf16_f32 v3, v87, s0
	v_lshl_add_u64 v[0:1], v[0:1], 0, s[52:53]
	global_store_short v[0:1], v3, off
	ds_read_b128 v[72:75], v149 offset:58880
	ds_read_b64_tr_b16 v[200:201], v199 offset:50176
	ds_read_b64_tr_b16 v[202:203], v199 offset:54528
	ds_read_b64_tr_b16 v[204:205], v199 offset:50208
	ds_read_b64_tr_b16 v[206:207], v199 offset:54560
	ds_read_b64_tr_b16 v[208:209], v199 offset:50240
	ds_read_b64_tr_b16 v[210:211], v199 offset:54592
	ds_read_b64_tr_b16 v[212:213], v199 offset:50272
	ds_read_b64_tr_b16 v[214:215], v199 offset:54624
	ds_read_b64_tr_b16 v[216:217], v199 offset:50304
	ds_read_b64_tr_b16 v[218:219], v199 offset:54656
	ds_read_b64_tr_b16 v[220:221], v199 offset:50336
	ds_read_b64_tr_b16 v[222:223], v199 offset:54688
	ds_read_b64_tr_b16 v[224:225], v199 offset:50368
	ds_read_b64_tr_b16 v[226:227], v199 offset:54720
	ds_read_b64_tr_b16 v[228:229], v199 offset:50400
	ds_read_b64_tr_b16 v[230:231], v199 offset:54752
	s_waitcnt lgkmcnt(14)
	v_mfma_f32_16x16x32_bf16 v[44:47], v[200:203], v[80:83], v[44:47]
	ds_read_b128 v[84:87], v149 offset:58944
	s_waitcnt lgkmcnt(13)
	v_mfma_f32_16x16x32_bf16 v[48:51], v[204:207], v[80:83], v[48:51]
	s_nop 4
	v_pk_mul_f32 v[46:47], v[74:75], v[46:47]
	v_pk_mul_f32 v[44:45], v[72:73], v[44:45]
	ds_read_b128 v[72:75], v149 offset:59008
	s_waitcnt lgkmcnt(1)
	v_pk_mul_f32 v[50:51], v[86:87], v[50:51]
	v_pk_mul_f32 v[48:49], v[84:85], v[48:49]
	v_mfma_f32_16x16x32_bf16 v[52:55], v[208:211], v[80:83], v[52:55]
	ds_read_b128 v[84:87], v149 offset:59072
	v_mfma_f32_16x16x32_bf16 v[56:59], v[212:215], v[80:83], v[56:59]
	s_nop 4
	s_waitcnt lgkmcnt(1)
	v_pk_mul_f32 v[54:55], v[74:75], v[54:55]
	v_pk_mul_f32 v[52:53], v[72:73], v[52:53]
	ds_read_b128 v[72:75], v149 offset:59136
	s_waitcnt lgkmcnt(1)
	v_pk_mul_f32 v[58:59], v[86:87], v[58:59]
	v_pk_mul_f32 v[56:57], v[84:85], v[56:57]
	v_mfma_f32_16x16x32_bf16 v[60:63], v[216:219], v[80:83], v[60:63]
	ds_read_b128 v[84:87], v149 offset:59200
	v_mfma_f32_16x16x32_bf16 v[64:67], v[220:223], v[80:83], v[64:67]
	s_nop 4
	s_waitcnt lgkmcnt(1)
	v_pk_mul_f32 v[62:63], v[74:75], v[62:63]
	v_pk_mul_f32 v[60:61], v[72:73], v[60:61]
	ds_read_b128 v[72:75], v149 offset:59264
	s_waitcnt lgkmcnt(1)
	v_pk_mul_f32 v[66:67], v[86:87], v[66:67]
	v_pk_mul_f32 v[64:65], v[84:85], v[64:65]
	v_mfma_f32_16x16x32_bf16 v[68:71], v[224:227], v[80:83], v[68:71]
	ds_read_b128 v[84:87], v149 offset:59328
	s_nop 5
	s_waitcnt lgkmcnt(1)
	v_pk_mul_f32 v[74:75], v[74:75], v[70:71]
	v_pk_mul_f32 v[72:73], v[72:73], v[68:69]
	v_mfma_f32_16x16x32_bf16 v[68:71], v[228:231], v[80:83], v[76:79]
	s_nop 6
	s_waitcnt lgkmcnt(0)
	v_pk_mul_f32 v[70:71], v[86:87], v[70:71]
	v_pk_mul_f32 v[68:69], v[84:85], v[68:69]
	s_cbranch_vccnz .LBB0_2411
	s_mov_b32 s76, s75
	s_branch .LBB0_2417
